# attention softmax max-tree: 53 canonicalizing v_max ops + s_nop 10 replaced by 16-op v_max3 tree (bit-identical)
# speedup vs baseline: 1.0241x; 1.0241x over previous
.LBB0_884:
	v_add_u32_e32 v1, 0x6000, v203
	v_lshl_add_u64 v[174:175], s[8:9], 0, v[164:165]
	v_readfirstlane_b32 s12, v1
	v_add_u32_e32 v1, 0x8000, v203
	v_lshl_add_u64 v[66:67], v[174:175], 0, s[0:1]
	s_mov_b32 m0, s12
	v_lshl_add_u64 v[176:177], s[8:9], 0, v[170:171]
	v_readfirstlane_b32 s12, v1
	v_add_u32_e32 v1, 0xa000, v203
	global_load_lds_dwordx4 v[66:67], off
	v_lshl_add_u64 v[66:67], v[176:177], 0, s[0:1]
	s_mov_b32 m0, s12
	v_lshl_add_u64 v[178:179], s[8:9], 0, v[168:169]
	v_readfirstlane_b32 s12, v1
	global_load_lds_dwordx4 v[66:67], off
	v_lshl_add_u64 v[66:67], v[178:179], 0, s[0:1]
	s_mov_b32 m0, s12
	v_cmp_le_u32_e32 vcc, s57, v207
	global_load_lds_dwordx4 v[66:67], off
	s_and_saveexec_b64 s[12:13], vcc
	s_cbranch_execz .LBB0_888
	v_mov_b32_e32 v1, v198
	v_mov_b32_e32 v154, v199
	s_nop 0
	v_add_u32_e32 v70, 0, v1
	ds_read_b128 v[66:69], v70
	ds_read_b128 v[70:73], v70 offset:8192
	s_waitcnt lgkmcnt(0)
	v_mfma_f32_32x32x16_bf16 v[82:97], v[66:69], v[98:101], 0
	v_xad_u32 v150, v1, 32, 0
	ds_read_b128 v[146:149], v150
	ds_read_b128 v[150:153], v150 offset:8192
	v_xad_u32 v155, v1, 64, 0
	v_mfma_f32_32x32x16_bf16 v[66:81], v[70:73], v[98:101], 0
	s_waitcnt lgkmcnt(0)
	v_mfma_f32_32x32x16_bf16 v[82:97], v[146:149], v[102:105], v[82:97]
	v_mfma_f32_32x32x16_bf16 v[66:81], v[150:153], v[102:105], v[66:81]
	ds_read_b128 v[146:149], v155
	ds_read_b128 v[150:153], v155 offset:8192
	s_waitcnt lgkmcnt(0)
	v_mfma_f32_32x32x16_bf16 v[82:97], v[146:149], v[106:109], v[82:97]
	v_xor_b32_e32 v146, 0x60, v1
	v_add_u32_e32 v155, 0, v146
	v_mfma_f32_32x32x16_bf16 v[66:81], v[150:153], v[106:109], v[66:81]
	ds_read_b128 v[146:149], v155
	ds_read_b128 v[150:153], v155 offset:8192
	s_waitcnt lgkmcnt(0)
	v_mfma_f32_32x32x16_bf16 v[82:97], v[146:149], v[110:113], v[82:97]
	v_xor_b32_e32 v146, 0x80, v1
	v_add_u32_e32 v155, 0, v146
	v_mfma_f32_32x32x16_bf16 v[66:81], v[150:153], v[110:113], v[66:81]
	ds_read_b128 v[146:149], v155
	ds_read_b128 v[150:153], v155 offset:8192
	s_waitcnt lgkmcnt(0)
	v_mfma_f32_32x32x16_bf16 v[82:97], v[146:149], v[122:125], v[82:97]
	v_xor_b32_e32 v146, 0xa0, v1
	v_add_u32_e32 v155, 0, v146
	v_mfma_f32_32x32x16_bf16 v[66:81], v[150:153], v[122:125], v[66:81]
	ds_read_b128 v[146:149], v155
	ds_read_b128 v[150:153], v155 offset:8192
	s_waitcnt lgkmcnt(0)
	v_mfma_f32_32x32x16_bf16 v[82:97], v[146:149], v[114:117], v[82:97]
	v_xor_b32_e32 v146, 0xc0, v1
	v_add_u32_e32 v155, 0, v146
	v_xor_b32_e32 v1, 0xe0, v1
	v_add_u32_e32 v1, 0, v1
	v_mfma_f32_32x32x16_bf16 v[66:81], v[150:153], v[114:117], v[66:81]
	ds_read_b128 v[146:149], v155
	ds_read_b128 v[150:153], v155 offset:8192
	s_waitcnt lgkmcnt(0)
	v_mfma_f32_32x32x16_bf16 v[82:97], v[146:149], v[118:121], v[82:97]
	v_mfma_f32_32x32x16_bf16 v[66:81], v[150:153], v[118:121], v[66:81]
	ds_read_b128 v[146:149], v1
	ds_read_b128 v[150:153], v1 offset:8192
	v_add_u32_e32 v1, 0, v154
	s_waitcnt lgkmcnt(0)
	v_mfma_f32_32x32x16_bf16 v[82:97], v[146:149], v[126:129], v[82:97]
	v_mfma_f32_32x32x16_bf16 v[66:81], v[150:153], v[126:129], v[66:81]
	ds_read_b128 v[146:149], v1
	ds_read_b128 v[150:153], v1 offset:4096
	v_xad_u32 v1, v154, 32, 0
	s_waitcnt lgkmcnt(0)
	v_mfma_f32_32x32x16_bf16 v[82:97], v[146:149], v[130:133], v[82:97]
	v_mfma_f32_32x32x16_bf16 v[66:81], v[150:153], v[130:133], v[66:81]
	ds_read_b128 v[146:149], v1
	ds_read_b128 v[150:153], v1 offset:4096
	v_xad_u32 v1, v154, 64, 0
	s_waitcnt lgkmcnt(0)
	v_mfma_f32_32x32x16_bf16 v[82:97], v[146:149], v[134:137], v[82:97]
	v_mfma_f32_32x32x16_bf16 v[66:81], v[150:153], v[134:137], v[66:81]
	ds_read_b128 v[146:149], v1
	ds_read_b128 v[150:153], v1 offset:4096
	v_xor_b32_e32 v1, 0x60, v154
	v_add_u32_e32 v1, 0, v1
	ds_read_b128 v[180:183], v1
	s_waitcnt lgkmcnt(0)
	v_mfma_f32_32x32x16_bf16 v[82:97], v[146:149], v[138:141], v[82:97]
	ds_read_b128 v[146:149], v1 offset:4096
	v_mfma_f32_32x32x16_bf16 v[66:81], v[150:153], v[138:141], v[66:81]
	s_waitcnt lgkmcnt(0)
	v_mfma_f32_32x32x16_bf16 v[66:81], v[146:149], v[142:145], v[66:81]
	ds_read_b64_tr_b16 v[158:159], v188 offset:0
	ds_read_b64_tr_b16 v[160:161], v189 offset:0
	ds_read_b64_tr_b16 v[154:155], v192 offset:0
	ds_read_b64_tr_b16 v[156:157], v193 offset:0
	ds_read_b64_tr_b16 v[150:151], v194 offset:0
	ds_read_b64_tr_b16 v[152:153], v195 offset:0
	ds_read_b64_tr_b16 v[146:147], v196 offset:0
	ds_read_b64_tr_b16 v[148:149], v197 offset:0
	v_mfma_f32_32x32x16_bf16 v[82:97], v[180:183], v[142:145], v[82:97]
	s_nop 4
	v_max3_f32 v1, v66, v67, v68
	v_max3_f32 v180, v69, v70, v71
	v_max3_f32 v1, v1, v72, v73
	v_max3_f32 v180, v180, v74, v75
	v_max3_f32 v1, v1, v76, v77
	v_max3_f32 v180, v180, v78, v79
	v_max3_f32 v1, v1, v80, v81
	v_max3_f32 v181, v82, v83, v84
	v_max3_f32 v182, v85, v86, v87
	v_max3_f32 v181, v181, v88, v89
	v_max3_f32 v182, v182, v90, v91
	v_max3_f32 v181, v181, v92, v93
	v_max3_f32 v182, v182, v94, v95
	v_max3_f32 v181, v181, v96, v97
	v_max3_f32 v1, v1, v180, v181
	v_max_f32_e32 v1, v1, v182
	v_mov_b32_e32 v180, v1
	s_nop 1
	v_permlane32_swap_b32_e32 v1, v180
	v_max_f32_e32 v1, v1, v180
	v_add_f32_e32 v180, 0x41000000, v208
	v_cmp_gt_f32_e32 vcc, v1, v180
	s_cbranch_vccz .LBB0_887
	v_max_f32_e32 v1, v1, v1
	v_max_f32_e32 v180, v208, v208
	v_max_f32_e32 v1, v180, v1
	v_sub_f32_e32 v180, v208, v1
	v_exp_f32_e32 v180, v180
	v_mov_b32_e32 v208, v1
	v_mul_f32_e32 v173, v173, v180
	v_pk_mul_f32 v[64:65], v[64:65], v[180:181] op_sel_hi:[1,0]
	v_pk_mul_f32 v[62:63], v[62:63], v[180:181] op_sel_hi:[1,0]
	v_pk_mul_f32 v[60:61], v[60:61], v[180:181] op_sel_hi:[1,0]
	v_pk_mul_f32 v[58:59], v[58:59], v[180:181] op_sel_hi:[1,0]
	v_pk_mul_f32 v[56:57], v[56:57], v[180:181] op_sel_hi:[1,0]
	v_pk_mul_f32 v[54:55], v[54:55], v[180:181] op_sel_hi:[1,0]
	v_pk_mul_f32 v[52:53], v[52:53], v[180:181] op_sel_hi:[1,0]
	v_pk_mul_f32 v[50:51], v[50:51], v[180:181] op_sel_hi:[1,0]
	v_pk_mul_f32 v[48:49], v[48:49], v[180:181] op_sel_hi:[1,0]
	v_pk_mul_f32 v[46:47], v[46:47], v[180:181] op_sel_hi:[1,0]
	v_pk_mul_f32 v[44:45], v[44:45], v[180:181] op_sel_hi:[1,0]
	v_pk_mul_f32 v[42:43], v[42:43], v[180:181] op_sel_hi:[1,0]
	v_pk_mul_f32 v[40:41], v[40:41], v[180:181] op_sel_hi:[1,0]
	v_pk_mul_f32 v[38:39], v[38:39], v[180:181] op_sel_hi:[1,0]
	v_pk_mul_f32 v[36:37], v[36:37], v[180:181] op_sel_hi:[1,0]
	v_pk_mul_f32 v[34:35], v[34:35], v[180:181] op_sel_hi:[1,0]
	v_pk_mul_f32 v[32:33], v[32:33], v[180:181] op_sel_hi:[1,0]
	v_pk_mul_f32 v[30:31], v[30:31], v[180:181] op_sel_hi:[1,0]
	v_pk_mul_f32 v[28:29], v[28:29], v[180:181] op_sel_hi:[1,0]
	v_pk_mul_f32 v[26:27], v[26:27], v[180:181] op_sel_hi:[1,0]
	v_pk_mul_f32 v[24:25], v[24:25], v[180:181] op_sel_hi:[1,0]
	v_pk_mul_f32 v[22:23], v[22:23], v[180:181] op_sel_hi:[1,0]
	v_pk_mul_f32 v[20:21], v[20:21], v[180:181] op_sel_hi:[1,0]
	v_pk_mul_f32 v[18:19], v[18:19], v[180:181] op_sel_hi:[1,0]
	v_pk_mul_f32 v[16:17], v[16:17], v[180:181] op_sel_hi:[1,0]
	v_pk_mul_f32 v[14:15], v[14:15], v[180:181] op_sel_hi:[1,0]
	v_pk_mul_f32 v[12:13], v[12:13], v[180:181] op_sel_hi:[1,0]
	v_pk_mul_f32 v[10:11], v[10:11], v[180:181] op_sel_hi:[1,0]
	v_pk_mul_f32 v[8:9], v[8:9], v[180:181] op_sel_hi:[1,0]
	v_pk_mul_f32 v[6:7], v[6:7], v[180:181] op_sel_hi:[1,0]
	v_pk_mul_f32 v[4:5], v[4:5], v[180:181] op_sel_hi:[1,0]
	v_pk_mul_f32 v[2:3], v[2:3], v[180:181] op_sel_hi:[1,0]

.LBB0_890:
	v_cmp_lt_u32_e32 vcc, s57, v207
	s_and_saveexec_b64 s[14:15], vcc
	s_cbranch_execz .LBB0_883
	v_mov_b32_e32 v1, v198
	v_mov_b32_e32 v154, v199
	s_nop 0
	v_add_u32_e32 v70, 0, v1
	ds_read_b128 v[66:69], v70 offset:24576
	ds_read_b128 v[70:73], v70 offset:32768
	s_waitcnt lgkmcnt(0)
	v_mfma_f32_32x32x16_bf16 v[82:97], v[66:69], v[98:101], 0
	v_xad_u32 v150, v1, 32, 0
	ds_read_b128 v[146:149], v150 offset:24576
	ds_read_b128 v[150:153], v150 offset:32768
	v_xad_u32 v155, v1, 64, 0
	v_mfma_f32_32x32x16_bf16 v[66:81], v[70:73], v[98:101], 0
	s_waitcnt lgkmcnt(0)
	v_mfma_f32_32x32x16_bf16 v[82:97], v[146:149], v[102:105], v[82:97]
	v_mfma_f32_32x32x16_bf16 v[66:81], v[150:153], v[102:105], v[66:81]
	ds_read_b128 v[146:149], v155 offset:24576
	ds_read_b128 v[150:153], v155 offset:32768
	s_waitcnt lgkmcnt(0)
	v_mfma_f32_32x32x16_bf16 v[82:97], v[146:149], v[106:109], v[82:97]
	v_xor_b32_e32 v146, 0x60, v1
	v_add_u32_e32 v155, 0, v146
	v_mfma_f32_32x32x16_bf16 v[66:81], v[150:153], v[106:109], v[66:81]
	ds_read_b128 v[146:149], v155 offset:24576
	ds_read_b128 v[150:153], v155 offset:32768
	s_waitcnt lgkmcnt(0)
	v_mfma_f32_32x32x16_bf16 v[82:97], v[146:149], v[110:113], v[82:97]
	v_xor_b32_e32 v146, 0x80, v1
	v_add_u32_e32 v155, 0, v146
	v_mfma_f32_32x32x16_bf16 v[66:81], v[150:153], v[110:113], v[66:81]
	ds_read_b128 v[146:149], v155 offset:24576
	ds_read_b128 v[150:153], v155 offset:32768
	s_waitcnt lgkmcnt(0)
	v_mfma_f32_32x32x16_bf16 v[82:97], v[146:149], v[122:125], v[82:97]
	v_xor_b32_e32 v146, 0xa0, v1
	v_add_u32_e32 v155, 0, v146
	v_mfma_f32_32x32x16_bf16 v[66:81], v[150:153], v[122:125], v[66:81]
	ds_read_b128 v[146:149], v155 offset:24576
	ds_read_b128 v[150:153], v155 offset:32768
	s_waitcnt lgkmcnt(0)
	v_mfma_f32_32x32x16_bf16 v[82:97], v[146:149], v[114:117], v[82:97]
	v_xor_b32_e32 v146, 0xc0, v1
	v_add_u32_e32 v155, 0, v146
	v_xor_b32_e32 v1, 0xe0, v1
	v_add_u32_e32 v1, 0, v1
	v_mfma_f32_32x32x16_bf16 v[66:81], v[150:153], v[114:117], v[66:81]
	ds_read_b128 v[146:149], v155 offset:24576
	ds_read_b128 v[150:153], v155 offset:32768
	s_waitcnt lgkmcnt(0)
	v_mfma_f32_32x32x16_bf16 v[82:97], v[146:149], v[118:121], v[82:97]
	v_mfma_f32_32x32x16_bf16 v[66:81], v[150:153], v[118:121], v[66:81]
	ds_read_b128 v[146:149], v1 offset:24576
	ds_read_b128 v[150:153], v1 offset:32768
	v_add_u32_e32 v1, 0, v154
	s_waitcnt lgkmcnt(0)
	v_mfma_f32_32x32x16_bf16 v[82:97], v[146:149], v[126:129], v[82:97]
	v_mfma_f32_32x32x16_bf16 v[66:81], v[150:153], v[126:129], v[66:81]
	ds_read_b128 v[146:149], v1 offset:24576
	ds_read_b128 v[150:153], v1 offset:28672
	v_xad_u32 v1, v154, 32, 0
	s_waitcnt lgkmcnt(0)
	v_mfma_f32_32x32x16_bf16 v[82:97], v[146:149], v[130:133], v[82:97]
	v_mfma_f32_32x32x16_bf16 v[66:81], v[150:153], v[130:133], v[66:81]
	ds_read_b128 v[146:149], v1 offset:24576
	ds_read_b128 v[150:153], v1 offset:28672
	v_xad_u32 v1, v154, 64, 0
	s_waitcnt lgkmcnt(0)
	v_mfma_f32_32x32x16_bf16 v[82:97], v[146:149], v[134:137], v[82:97]
	v_mfma_f32_32x32x16_bf16 v[66:81], v[150:153], v[134:137], v[66:81]
	ds_read_b128 v[146:149], v1 offset:24576
	ds_read_b128 v[150:153], v1 offset:28672
	v_xor_b32_e32 v1, 0x60, v154
	v_add_u32_e32 v1, 0, v1
	ds_read_b128 v[174:177], v1 offset:24576
	s_waitcnt lgkmcnt(0)
	v_mfma_f32_32x32x16_bf16 v[82:97], v[146:149], v[138:141], v[82:97]
	ds_read_b128 v[146:149], v1 offset:28672
	v_mfma_f32_32x32x16_bf16 v[66:81], v[150:153], v[138:141], v[66:81]
	s_waitcnt lgkmcnt(0)
	v_mfma_f32_32x32x16_bf16 v[66:81], v[146:149], v[142:145], v[66:81]
	ds_read_b64_tr_b16 v[158:159], v188 offset:0x6000
	ds_read_b64_tr_b16 v[160:161], v189 offset:0x6000
	ds_read_b64_tr_b16 v[154:155], v192 offset:0x6000
	ds_read_b64_tr_b16 v[156:157], v193 offset:0x6000
	ds_read_b64_tr_b16 v[150:151], v194 offset:0x6000
	ds_read_b64_tr_b16 v[152:153], v195 offset:0x6000
	ds_read_b64_tr_b16 v[146:147], v196 offset:0x6000
	ds_read_b64_tr_b16 v[148:149], v197 offset:0x6000
	v_mfma_f32_32x32x16_bf16 v[82:97], v[174:177], v[142:145], v[82:97]
	s_nop 4
	v_max3_f32 v1, v66, v67, v68
	v_max3_f32 v174, v69, v70, v71
	v_max3_f32 v1, v1, v72, v73
	v_max3_f32 v174, v174, v74, v75
	v_max3_f32 v1, v1, v76, v77
	v_max3_f32 v174, v174, v78, v79
	v_max3_f32 v1, v1, v80, v81
	v_max3_f32 v175, v82, v83, v84
	v_max3_f32 v176, v85, v86, v87
	v_max3_f32 v175, v175, v88, v89
	v_max3_f32 v176, v176, v90, v91
	v_max3_f32 v175, v175, v92, v93
	v_max3_f32 v176, v176, v94, v95
	v_max3_f32 v175, v175, v96, v97
	v_max3_f32 v1, v1, v174, v175
	v_max_f32_e32 v1, v1, v176
	v_mov_b32_e32 v174, v1
	s_nop 1
	v_permlane32_swap_b32_e32 v1, v174
	v_max_f32_e32 v1, v1, v174
	v_add_f32_e32 v174, 0x41000000, v208
	v_cmp_gt_f32_e32 vcc, v1, v174
	s_cbranch_vccz .LBB0_882
	v_max_f32_e32 v1, v1, v1
	v_max_f32_e32 v174, v208, v208
	v_max_f32_e32 v1, v174, v1
	v_sub_f32_e32 v174, v208, v1
	v_exp_f32_e32 v174, v174
	v_mov_b32_e32 v208, v1
	v_mul_f32_e32 v173, v173, v174
	v_pk_mul_f32 v[64:65], v[64:65], v[174:175] op_sel_hi:[1,0]
	v_pk_mul_f32 v[62:63], v[62:63], v[174:175] op_sel_hi:[1,0]
	v_pk_mul_f32 v[60:61], v[60:61], v[174:175] op_sel_hi:[1,0]
	v_pk_mul_f32 v[58:59], v[58:59], v[174:175] op_sel_hi:[1,0]
	v_pk_mul_f32 v[56:57], v[56:57], v[174:175] op_sel_hi:[1,0]
	v_pk_mul_f32 v[54:55], v[54:55], v[174:175] op_sel_hi:[1,0]
	v_pk_mul_f32 v[52:53], v[52:53], v[174:175] op_sel_hi:[1,0]
	v_pk_mul_f32 v[50:51], v[50:51], v[174:175] op_sel_hi:[1,0]
	v_pk_mul_f32 v[48:49], v[48:49], v[174:175] op_sel_hi:[1,0]
	v_pk_mul_f32 v[46:47], v[46:47], v[174:175] op_sel_hi:[1,0]
	v_pk_mul_f32 v[44:45], v[44:45], v[174:175] op_sel_hi:[1,0]
	v_pk_mul_f32 v[42:43], v[42:43], v[174:175] op_sel_hi:[1,0]
	v_pk_mul_f32 v[40:41], v[40:41], v[174:175] op_sel_hi:[1,0]
	v_pk_mul_f32 v[38:39], v[38:39], v[174:175] op_sel_hi:[1,0]
	v_pk_mul_f32 v[36:37], v[36:37], v[174:175] op_sel_hi:[1,0]
	v_pk_mul_f32 v[34:35], v[34:35], v[174:175] op_sel_hi:[1,0]
	v_pk_mul_f32 v[32:33], v[32:33], v[174:175] op_sel_hi:[1,0]
	v_pk_mul_f32 v[30:31], v[30:31], v[174:175] op_sel_hi:[1,0]
	v_pk_mul_f32 v[28:29], v[28:29], v[174:175] op_sel_hi:[1,0]
	v_pk_mul_f32 v[26:27], v[26:27], v[174:175] op_sel_hi:[1,0]
	v_pk_mul_f32 v[24:25], v[24:25], v[174:175] op_sel_hi:[1,0]
	v_pk_mul_f32 v[22:23], v[22:23], v[174:175] op_sel_hi:[1,0]
	v_pk_mul_f32 v[20:21], v[20:21], v[174:175] op_sel_hi:[1,0]
	v_pk_mul_f32 v[18:19], v[18:19], v[174:175] op_sel_hi:[1,0]
	v_pk_mul_f32 v[16:17], v[16:17], v[174:175] op_sel_hi:[1,0]
	v_pk_mul_f32 v[14:15], v[14:15], v[174:175] op_sel_hi:[1,0]
	v_pk_mul_f32 v[12:13], v[12:13], v[174:175] op_sel_hi:[1,0]
	v_pk_mul_f32 v[10:11], v[10:11], v[174:175] op_sel_hi:[1,0]
	v_pk_mul_f32 v[8:9], v[8:9], v[174:175] op_sel_hi:[1,0]
	v_pk_mul_f32 v[6:7], v[6:7], v[174:175] op_sel_hi:[1,0]
	v_pk_mul_f32 v[4:5], v[4:5], v[174:175] op_sel_hi:[1,0]
	v_pk_mul_f32 v[2:3], v[2:3], v[174:175] op_sel_hi:[1,0]
	s_branch .LBB0_882
